# resid+norm fused epilogue: x/gate loads hoisted 16-deep with counted vmcnt instead of 32 serialized load-wait-fma-store steps
# speedup vs baseline: 1.0085x; 1.0085x over previous
;     __device__ __forceinline__ void fused(f32x4 (&acc)[2][2][4][2], const Unit& u, int wr, int wc, int fr, int fq, ldsp lds, int wid, int lane) const {
;         const int rowt = u.pm * BM, b = rowt >> 11;
;         const char* xsb = (const char*)(xs + (size_t)rowt * D + u.pn * BM);
;         char* xdb = (char*)(xd + (size_t)rowt * D + u.pn * BM);
;         const char* gp = (const char*)(gate + (size_t)b * NMOD + u.pn * BM);
;         const unsigned coff = (unsigned)(wc * 32 + 4 * fq) * 4u;
;         unsigned off0 = (unsigned)(wr * 64 + fr) * (D * 4u) + coff; asm volatile("" : "+v"(off0));
; #pragma unroll
;         for (int bj = 0; bj < 2; ++bj)
; #pragma unroll
;             for (int n = 0; n < 2; ++n) { const f32x4 gv = *(const f32x4*)(gp + coff + (bj * HALF + n * 16) * 4);
; #pragma unroll
;                 for (int ai = 0; ai < 2; ++ai) {
; #pragma unroll
;                     for (int m = 0; m < 4; ++m) { const unsigned off = off0 + (unsigned)((ai * HALF + m * 16) * D + bj * HALF + n * 16) * 4u;
;                         const f32x4 xv = *(const f32x4*)(xsb + off); acc[ai][bj][m][n] = xv + gv * acc[ai][bj][m][n];
;                         if (!fin) *(f32x4*)(xdb + off) = acc[ai][bj][m][n]; }
;                     asm volatile("" ::: "memory"); } }
.LBB0_352:
	v_readlane_b32 s8, v255, 19
	s_lshl_b32 s5, s8, 2
	v_readlane_b32 s8, v254, 30
	s_add_u32 s5, s8, s5
	v_readlane_b32 s8, v254, 31
	v_readlane_b32 s9, v255, 20
	s_addc_u32 s24, s8, 0
	s_lshl_b32 s8, s3, 8
	s_ashr_i32 s9, s8, 31
	s_ashr_i32 s25, s3, 3
	s_lshl_b64 s[10:11], s[8:9], 12
	v_readlane_b32 s12, v254, 32
	v_readlane_b32 s13, v254, 33
	s_add_u32 s9, s12, s10
	s_addc_u32 s12, s13, s11
	s_lshl_b32 s14, s40, 8
	s_ashr_i32 s15, s14, 31
	s_lshl_b64 s[22:23], s[14:15], 2
	s_add_u32 s42, s9, s22
	s_addc_u32 s43, s12, s23
	s_add_u32 s9, s54, s10
	s_addc_u32 s10, s55, s11
	s_add_u32 s12, s9, s22
	s_addc_u32 s13, s10, s23
	s_mul_hi_i32 s11, s25, 0x1800
	s_mul_i32 s10, s25, 0x1800
	s_lshl_b64 s[30:31], s[10:11], 2
	v_lshl_or_b32 v149, s4, 5, v161
	s_add_u32 s5, s5, s30
	v_lshlrev_b32_e32 v146, 2, v149
	s_addc_u32 s9, s24, s31
	v_lshl_or_b32 v96, v148, 12, v146
	s_add_u32 s22, s5, s22
	s_addc_u32 s23, s9, s23
	v_add_u32_e32 v147, 0x10000, v96
	v_add_u32_e32 v194, 0x20000, v96
	v_add_u32_e32 v195, 0x30000, v96
	v_add_u32_e32 v197, 0x80000, v96
	v_add_u32_e32 v198, 0x90000, v96
	v_add_u32_e32 v199, 0xa0000, v96
	v_add_u32_e32 v200, 0xb0000, v96
	global_load_dwordx4 v[142:145], v146, s[22:23]
	global_load_dwordx4 v[150:153], v146, s[22:23] offset:64
	global_load_dwordx4 v[190:193], v146, s[22:23] offset:512
	global_load_dwordx4 v[162:165], v96, s[42:43]
	global_load_dwordx4 v[166:169], v147, s[42:43]
	global_load_dwordx4 v[170:173], v194, s[42:43]
	global_load_dwordx4 v[174:177], v195, s[42:43]
	global_load_dwordx4 v[178:181], v197, s[42:43]
	global_load_dwordx4 v[182:185], v198, s[42:43]
	global_load_dwordx4 v[226:229], v199, s[42:43]
	global_load_dwordx4 v[230:233], v200, s[42:43]
	global_load_dwordx4 v[234:237], v96, s[42:43] offset:64
	global_load_dwordx4 v[238:241], v147, s[42:43] offset:64
	global_load_dwordx4 v[242:245], v194, s[42:43] offset:64
	global_load_dwordx4 v[246:249], v195, s[42:43] offset:64
	global_load_dwordx4 v[250:253], v197, s[42:43] offset:64
	global_load_dwordx4 v[202:205], v198, s[42:43] offset:64
	global_load_dwordx4 v[206:209], v199, s[42:43] offset:64
	global_load_dwordx4 v[210:213], v200, s[42:43] offset:64
	s_waitcnt vmcnt(19)
	s_barrier
	v_cndmask_b32_e64 v134, 0, 1, s[84:85]
	v_cmp_ne_u32_e64 s[10:11], 1, v134
	v_readlane_b32 s36, v255, 14
	v_readlane_b32 s44, v255, 0
	s_mov_b32 s64, 0x41000000
	v_readlane_b32 s65, v254, 51
	v_readlane_b32 s37, v255, 15
	v_readlane_b32 s45, v255, 1
	s_andn2_b64 vcc, exec, s[84:85]
	s_cbranch_vccnz .Lrn_ladder_fin
	s_waitcnt vmcnt(15)
	v_pk_fma_f32 v[140:141], v[128:129], v[144:145], v[164:165]
	v_pk_fma_f32 v[138:139], v[126:127], v[142:143], v[162:163]
	global_store_dwordx4 v96, v[138:141], s[12:13]
	global_load_dwordx4 v[162:165], v96, s[42:43] offset:512
	s_waitcnt vmcnt(16)
	v_pk_fma_f32 v[136:137], v[124:125], v[144:145], v[168:169]
	v_pk_fma_f32 v[134:135], v[122:123], v[142:143], v[166:167]
	global_store_dwordx4 v147, v[134:137], s[12:13]
	global_load_dwordx4 v[166:169], v147, s[42:43] offset:512
	s_waitcnt vmcnt(17)
	v_pk_fma_f32 v[132:133], v[116:117], v[144:145], v[172:173]
	v_pk_fma_f32 v[130:131], v[114:115], v[142:143], v[170:171]
	global_store_dwordx4 v194, v[130:133], s[12:13]
	global_load_dwordx4 v[170:173], v194, s[42:43] offset:512
	s_waitcnt vmcnt(18)
	v_pk_fma_f32 v[128:129], v[108:109], v[144:145], v[176:177]
	v_pk_fma_f32 v[126:127], v[106:107], v[142:143], v[174:175]
	global_store_dwordx4 v195, v[126:129], s[12:13]
	global_load_dwordx4 v[174:177], v195, s[42:43] offset:512
	s_waitcnt vmcnt(19)
	v_pk_fma_f32 v[124:125], v[100:101], v[144:145], v[180:181]
	v_pk_fma_f32 v[122:123], v[98:99], v[142:143], v[178:179]
	global_store_dwordx4 v197, v[122:125], s[12:13]
	global_load_dwordx4 v[178:181], v197, s[42:43] offset:512
	s_waitcnt vmcnt(20)
	v_pk_fma_f32 v[116:117], v[90:91], v[144:145], v[184:185]
	v_pk_fma_f32 v[114:115], v[88:89], v[142:143], v[182:183]
	global_store_dwordx4 v198, v[114:117], s[12:13]
	global_load_dwordx4 v[182:185], v198, s[42:43] offset:512
	s_waitcnt vmcnt(21)
	v_pk_fma_f32 v[108:109], v[82:83], v[144:145], v[228:229]
	v_pk_fma_f32 v[106:107], v[80:81], v[142:143], v[226:227]
	global_store_dwordx4 v199, v[106:109], s[12:13]
	global_load_dwordx4 v[226:229], v199, s[42:43] offset:512
	s_waitcnt vmcnt(22)
	v_pk_fma_f32 v[100:101], v[74:75], v[144:145], v[232:233]
	v_pk_fma_f32 v[98:99], v[72:73], v[142:143], v[230:231]
	global_store_dwordx4 v200, v[98:101], s[12:13]
	global_load_dwordx4 v[230:233], v200, s[42:43] offset:512
	global_load_dwordx4 v[142:145], v146, s[22:23] offset:576
	s_waitcnt vmcnt(24)
	v_pk_fma_f32 v[94:95], v[94:95], v[152:153], v[236:237]
	v_pk_fma_f32 v[92:93], v[92:93], v[150:151], v[234:235]
	global_store_dwordx4 v96, v[92:95], s[12:13] offset:64
	global_load_dwordx4 v[234:237], v96, s[42:43] offset:576
	s_waitcnt vmcnt(25)
	v_pk_fma_f32 v[90:91], v[86:87], v[152:153], v[240:241]
	v_pk_fma_f32 v[88:89], v[84:85], v[150:151], v[238:239]
	global_store_dwordx4 v147, v[88:91], s[12:13] offset:64
	global_load_dwordx4 v[238:241], v147, s[42:43] offset:576
	s_waitcnt vmcnt(26)
	v_pk_fma_f32 v[86:87], v[78:79], v[152:153], v[244:245]
	v_pk_fma_f32 v[84:85], v[76:77], v[150:151], v[242:243]
	global_store_dwordx4 v194, v[84:87], s[12:13] offset:64
	global_load_dwordx4 v[242:245], v194, s[42:43] offset:576
	s_waitcnt vmcnt(27)
	v_pk_fma_f32 v[82:83], v[70:71], v[152:153], v[248:249]
	v_pk_fma_f32 v[80:81], v[68:69], v[150:151], v[246:247]
	global_store_dwordx4 v195, v[80:83], s[12:13] offset:64
	global_load_dwordx4 v[246:249], v195, s[42:43] offset:576
	s_waitcnt vmcnt(28)
;     __device__ __forceinline__ void fused(f32x4 (&acc)[2][2][4][2], const Unit& u, int wr, int wc, int fr, int fq, ldsp lds, int wid, int lane) const {
;     ...
;         for (int bj = 0; bj < 2; ++bj)
; #pragma unroll
;             for (int n = 0; n < 2; ++n) { const f32x4 gv = *(const f32x4*)(gp + coff + (bj * HALF + n * 16) * 4);
; #pragma unroll
;                 for (int ai = 0; ai < 2; ++ai) {
; #pragma unroll
;                     for (int m = 0; m < 4; ++m) { const unsigned off = off0 + (unsigned)((ai * HALF + m * 16) * D + bj * HALF + n * 16) * 4u;
;                         const f32x4 xv = *(const f32x4*)(xsb + off); acc[ai][bj][m][n] = xv + gv * acc[ai][bj][m][n];
;                         if (!fin) *(f32x4*)(xdb + off) = acc[ai][bj][m][n]; }
;                     asm volatile("" ::: "memory"); } }
	v_pk_fma_f32 v[78:79], v[66:67], v[152:153], v[252:253]
	v_pk_fma_f32 v[76:77], v[64:65], v[150:151], v[250:251]
	global_store_dwordx4 v197, v[76:79], s[12:13] offset:64
	global_load_dwordx4 v[250:253], v197, s[42:43] offset:576
	s_waitcnt vmcnt(29)
	v_pk_fma_f32 v[74:75], v[62:63], v[152:153], v[204:205]
	v_pk_fma_f32 v[72:73], v[60:61], v[150:151], v[202:203]
	global_store_dwordx4 v198, v[72:75], s[12:13] offset:64
	global_load_dwordx4 v[202:205], v198, s[42:43] offset:576
	s_waitcnt vmcnt(30)
	v_pk_fma_f32 v[70:71], v[54:55], v[152:153], v[208:209]
	v_pk_fma_f32 v[68:69], v[52:53], v[150:151], v[206:207]
	global_store_dwordx4 v199, v[68:71], s[12:13] offset:64
	global_load_dwordx4 v[206:209], v199, s[42:43] offset:576
	s_waitcnt vmcnt(31)
	v_pk_fma_f32 v[66:67], v[46:47], v[152:153], v[212:213]
	v_pk_fma_f32 v[64:65], v[44:45], v[150:151], v[210:211]
	global_store_dwordx4 v200, v[64:67], s[12:13] offset:64
	global_load_dwordx4 v[210:213], v200, s[42:43] offset:576
	s_waitcnt vmcnt(31)
	v_pk_fma_f32 v[62:63], v[58:59], v[192:193], v[164:165]
	v_pk_fma_f32 v[60:61], v[56:57], v[190:191], v[162:163]
	global_store_dwordx4 v96, v[60:63], s[12:13] offset:512
	s_waitcnt vmcnt(30)
	v_pk_fma_f32 v[58:59], v[50:51], v[192:193], v[168:169]
	v_pk_fma_f32 v[56:57], v[48:49], v[190:191], v[166:167]
	global_store_dwordx4 v147, v[56:59], s[12:13] offset:512
	s_waitcnt vmcnt(29)
	v_pk_fma_f32 v[54:55], v[42:43], v[192:193], v[172:173]
	v_pk_fma_f32 v[52:53], v[40:41], v[190:191], v[170:171]
	global_store_dwordx4 v194, v[52:55], s[12:13] offset:512
	s_waitcnt vmcnt(28)
	v_pk_fma_f32 v[50:51], v[38:39], v[192:193], v[176:177]
	v_pk_fma_f32 v[48:49], v[36:37], v[190:191], v[174:175]
	global_store_dwordx4 v195, v[48:51], s[12:13] offset:512
	s_waitcnt vmcnt(27)
	v_pk_fma_f32 v[46:47], v[34:35], v[192:193], v[180:181]
	v_pk_fma_f32 v[44:45], v[32:33], v[190:191], v[178:179]
	global_store_dwordx4 v197, v[44:47], s[12:13] offset:512
	s_waitcnt vmcnt(26)
	v_pk_fma_f32 v[42:43], v[30:31], v[192:193], v[184:185]
	v_pk_fma_f32 v[40:41], v[28:29], v[190:191], v[182:183]
	global_store_dwordx4 v198, v[40:43], s[12:13] offset:512
	s_waitcnt vmcnt(25)
	v_pk_fma_f32 v[38:39], v[26:27], v[192:193], v[228:229]
	v_pk_fma_f32 v[36:37], v[24:25], v[190:191], v[226:227]
	global_store_dwordx4 v199, v[36:39], s[12:13] offset:512
	s_waitcnt vmcnt(24)
	v_pk_fma_f32 v[34:35], v[22:23], v[192:193], v[232:233]
	v_pk_fma_f32 v[32:33], v[20:21], v[190:191], v[230:231]
	global_store_dwordx4 v200, v[32:35], s[12:13] offset:512
	s_waitcnt vmcnt(22)
	v_pk_fma_f32 v[30:31], v[120:121], v[144:145], v[236:237]
	v_pk_fma_f32 v[28:29], v[118:119], v[142:143], v[234:235]
	global_store_dwordx4 v96, v[28:31], s[12:13] offset:576
	s_waitcnt vmcnt(21)
	v_pk_fma_f32 v[26:27], v[112:113], v[144:145], v[240:241]
	v_pk_fma_f32 v[24:25], v[110:111], v[142:143], v[238:239]
	global_store_dwordx4 v147, v[24:27], s[12:13] offset:576
	s_waitcnt vmcnt(20)
	v_pk_fma_f32 v[22:23], v[104:105], v[144:145], v[244:245]
	v_pk_fma_f32 v[20:21], v[102:103], v[142:143], v[242:243]
	global_store_dwordx4 v194, v[20:23], s[12:13] offset:576
	s_waitcnt vmcnt(19)
	v_pk_fma_f32 v[18:19], v[18:19], v[144:145], v[248:249]
	v_pk_fma_f32 v[16:17], v[16:17], v[142:143], v[246:247]
	global_store_dwordx4 v195, v[16:19], s[12:13] offset:576
	s_waitcnt vmcnt(18)
	v_pk_fma_f32 v[14:15], v[14:15], v[144:145], v[252:253]
	v_pk_fma_f32 v[12:13], v[12:13], v[142:143], v[250:251]
	global_store_dwordx4 v197, v[12:15], s[12:13] offset:576
	s_waitcnt vmcnt(17)
	v_pk_fma_f32 v[10:11], v[10:11], v[144:145], v[204:205]
	v_pk_fma_f32 v[8:9], v[8:9], v[142:143], v[202:203]
	global_store_dwordx4 v198, v[8:11], s[12:13] offset:576
	s_waitcnt vmcnt(16)
	v_pk_fma_f32 v[6:7], v[6:7], v[144:145], v[208:209]
	v_pk_fma_f32 v[4:5], v[4:5], v[142:143], v[206:207]
	global_store_dwordx4 v199, v[4:7], s[12:13] offset:576
	s_waitcnt vmcnt(15)
	v_pk_fma_f32 v[2:3], v[2:3], v[144:145], v[212:213]
	v_pk_fma_f32 v[0:1], v[0:1], v[142:143], v[210:211]
	global_store_dwordx4 v200, v[0:3], s[12:13] offset:576
	s_branch .Lrn_ladder_done
; #define LAS __attribute__((address_space(3)))
;     __device__ __forceinline__ void fused(f32x4 (&acc)[2][2][4][2], const Unit& u, int wr, int wc, int fr, int fq, ldsp lds, int wid, int lane) const {
;     ...
;         for (int bj = 0; bj < 2; ++bj)
; #pragma unroll
;             for (int n = 0; n < 2; ++n) { const f32x4 gv = *(const f32x4*)(gp + coff + (bj * HALF + n * 16) * 4);
; #pragma unroll
;                 for (int ai = 0; ai < 2; ++ai) {
; #pragma unroll
;                     for (int m = 0; m < 4; ++m) { const unsigned off = off0 + (unsigned)((ai * HALF + m * 16) * D + bj * HALF + n * 16) * 4u;
;                         const f32x4 xv = *(const f32x4*)(xsb + off); acc[ai][bj][m][n] = xv + gv * acc[ai][bj][m][n];
;                         if (!fin) *(f32x4*)(xdb + off) = acc[ai][bj][m][n]; }
;                     asm volatile("" ::: "memory"); } }
;         LAS float* P = (LAS float*)lds;
;         LAS float* Sx = (LAS float*)(lds + 4096);
; #pragma unroll
;         for (int ai = 0; ai < 2; ++ai)
; #pragma unroll
;             for (int m = 0; m < 4; ++m) { float sq = 0.f;
; #pragma unroll
;                 for (int bj = 0; bj < 2; ++bj)
; #pragma unroll
;                     for (int n = 0; n < 2; ++n) { const f32x4 v = acc[ai][bj][m][n]; sq += (v[0] * v[0] + v[1] * v[1]) + (v[2] * v[2] + v[3] * v[3]); }
;                 sq += __shfl_xor(sq, 16); sq += __shfl_xor(sq, 32);
;                 if (fq == 0) P[(ai * HALF + wr * 64 + m * 16 + fr) * 4 + wc] = sq; }
.Lrn_ladder_fin:
	s_waitcnt vmcnt(15)
	v_pk_fma_f32 v[140:141], v[128:129], v[144:145], v[164:165]
	v_pk_fma_f32 v[138:139], v[126:127], v[142:143], v[162:163]
	global_load_dwordx4 v[162:165], v96, s[42:43] offset:512
	s_waitcnt vmcnt(15)
	v_pk_fma_f32 v[136:137], v[124:125], v[144:145], v[168:169]
	v_pk_fma_f32 v[134:135], v[122:123], v[142:143], v[166:167]
	global_load_dwordx4 v[166:169], v147, s[42:43] offset:512
	s_waitcnt vmcnt(15)
	v_pk_fma_f32 v[132:133], v[116:117], v[144:145], v[172:173]
	v_pk_fma_f32 v[130:131], v[114:115], v[142:143], v[170:171]
	global_load_dwordx4 v[170:173], v194, s[42:43] offset:512
	s_waitcnt vmcnt(15)
	v_pk_fma_f32 v[128:129], v[108:109], v[144:145], v[176:177]
	v_pk_fma_f32 v[126:127], v[106:107], v[142:143], v[174:175]
	global_load_dwordx4 v[174:177], v195, s[42:43] offset:512
	s_waitcnt vmcnt(15)
	v_pk_fma_f32 v[124:125], v[100:101], v[144:145], v[180:181]
	v_pk_fma_f32 v[122:123], v[98:99], v[142:143], v[178:179]
	global_load_dwordx4 v[178:181], v197, s[42:43] offset:512
	s_waitcnt vmcnt(15)
	v_pk_fma_f32 v[116:117], v[90:91], v[144:145], v[184:185]
	v_pk_fma_f32 v[114:115], v[88:89], v[142:143], v[182:183]
	global_load_dwordx4 v[182:185], v198, s[42:43] offset:512
	s_waitcnt vmcnt(15)
	v_pk_fma_f32 v[108:109], v[82:83], v[144:145], v[228:229]
	v_pk_fma_f32 v[106:107], v[80:81], v[142:143], v[226:227]
	global_load_dwordx4 v[226:229], v199, s[42:43] offset:512
	s_waitcnt vmcnt(15)
	v_pk_fma_f32 v[100:101], v[74:75], v[144:145], v[232:233]
	v_pk_fma_f32 v[98:99], v[72:73], v[142:143], v[230:231]
	global_load_dwordx4 v[230:233], v200, s[42:43] offset:512
	global_load_dwordx4 v[142:145], v146, s[22:23] offset:576
	s_waitcnt vmcnt(16)
	v_pk_fma_f32 v[94:95], v[94:95], v[152:153], v[236:237]
	v_pk_fma_f32 v[92:93], v[92:93], v[150:151], v[234:235]
	global_load_dwordx4 v[234:237], v96, s[42:43] offset:576
	s_waitcnt vmcnt(16)
	v_pk_fma_f32 v[90:91], v[86:87], v[152:153], v[240:241]
	v_pk_fma_f32 v[88:89], v[84:85], v[150:151], v[238:239]
	global_load_dwordx4 v[238:241], v147, s[42:43] offset:576
	s_waitcnt vmcnt(16)
	v_pk_fma_f32 v[86:87], v[78:79], v[152:153], v[244:245]
	v_pk_fma_f32 v[84:85], v[76:77], v[150:151], v[242:243]
	global_load_dwordx4 v[242:245], v194, s[42:43] offset:576
	s_waitcnt vmcnt(16)
	v_pk_fma_f32 v[82:83], v[70:71], v[152:153], v[248:249]
	v_pk_fma_f32 v[80:81], v[68:69], v[150:151], v[246:247]
	global_load_dwordx4 v[246:249], v195, s[42:43] offset:576
	s_waitcnt vmcnt(16)
	v_pk_fma_f32 v[78:79], v[66:67], v[152:153], v[252:253]
	v_pk_fma_f32 v[76:77], v[64:65], v[150:151], v[250:251]
	global_load_dwordx4 v[250:253], v197, s[42:43] offset:576
	s_waitcnt vmcnt(16)
	v_pk_fma_f32 v[74:75], v[62:63], v[152:153], v[204:205]
	v_pk_fma_f32 v[72:73], v[60:61], v[150:151], v[202:203]
	global_load_dwordx4 v[202:205], v198, s[42:43] offset:576
	s_waitcnt vmcnt(16)
	v_pk_fma_f32 v[70:71], v[54:55], v[152:153], v[208:209]
	v_pk_fma_f32 v[68:69], v[52:53], v[150:151], v[206:207]
	global_load_dwordx4 v[206:209], v199, s[42:43] offset:576
	s_waitcnt vmcnt(16)
	v_pk_fma_f32 v[66:67], v[46:47], v[152:153], v[212:213]
	v_pk_fma_f32 v[64:65], v[44:45], v[150:151], v[210:211]
	global_load_dwordx4 v[210:213], v200, s[42:43] offset:576
	s_waitcnt vmcnt(16)
	v_pk_fma_f32 v[62:63], v[58:59], v[192:193], v[164:165]
	v_pk_fma_f32 v[60:61], v[56:57], v[190:191], v[162:163]
	s_waitcnt vmcnt(15)
	v_pk_fma_f32 v[58:59], v[50:51], v[192:193], v[168:169]
	v_pk_fma_f32 v[56:57], v[48:49], v[190:191], v[166:167]
	s_waitcnt vmcnt(14)
	v_pk_fma_f32 v[54:55], v[42:43], v[192:193], v[172:173]
	v_pk_fma_f32 v[52:53], v[40:41], v[190:191], v[170:171]
	s_waitcnt vmcnt(13)
	v_pk_fma_f32 v[50:51], v[38:39], v[192:193], v[176:177]
	v_pk_fma_f32 v[48:49], v[36:37], v[190:191], v[174:175]
	s_waitcnt vmcnt(12)
	v_pk_fma_f32 v[46:47], v[34:35], v[192:193], v[180:181]
	v_pk_fma_f32 v[44:45], v[32:33], v[190:191], v[178:179]
	s_waitcnt vmcnt(11)
	v_pk_fma_f32 v[42:43], v[30:31], v[192:193], v[184:185]
	v_pk_fma_f32 v[40:41], v[28:29], v[190:191], v[182:183]
	s_waitcnt vmcnt(10)
	v_pk_fma_f32 v[38:39], v[26:27], v[192:193], v[228:229]
	v_pk_fma_f32 v[36:37], v[24:25], v[190:191], v[226:227]
	s_waitcnt vmcnt(9)
	v_pk_fma_f32 v[34:35], v[22:23], v[192:193], v[232:233]
	v_pk_fma_f32 v[32:33], v[20:21], v[190:191], v[230:231]
	s_waitcnt vmcnt(7)
	v_pk_fma_f32 v[30:31], v[120:121], v[144:145], v[236:237]
	v_pk_fma_f32 v[28:29], v[118:119], v[142:143], v[234:235]
	s_waitcnt vmcnt(6)
	v_pk_fma_f32 v[26:27], v[112:113], v[144:145], v[240:241]
	v_pk_fma_f32 v[24:25], v[110:111], v[142:143], v[238:239]
	s_waitcnt vmcnt(5)
	v_pk_fma_f32 v[22:23], v[104:105], v[144:145], v[244:245]
	v_pk_fma_f32 v[20:21], v[102:103], v[142:143], v[242:243]
	s_waitcnt vmcnt(4)
	v_pk_fma_f32 v[18:19], v[18:19], v[144:145], v[248:249]
	v_pk_fma_f32 v[16:17], v[16:17], v[142:143], v[246:247]
	s_waitcnt vmcnt(3)
	v_pk_fma_f32 v[14:15], v[14:15], v[144:145], v[252:253]
	v_pk_fma_f32 v[12:13], v[12:13], v[142:143], v[250:251]
	s_waitcnt vmcnt(2)
	v_pk_fma_f32 v[10:11], v[10:11], v[144:145], v[204:205]
	v_pk_fma_f32 v[8:9], v[8:9], v[142:143], v[202:203]
	s_waitcnt vmcnt(1)
	v_pk_fma_f32 v[6:7], v[6:7], v[144:145], v[208:209]
	v_pk_fma_f32 v[4:5], v[4:5], v[142:143], v[206:207]
	s_waitcnt vmcnt(0)
	v_pk_fma_f32 v[2:3], v[2:3], v[144:145], v[212:213]
	v_pk_fma_f32 v[0:1], v[0:1], v[142:143], v[210:211]
.Lrn_ladder_done:
	s_andn2_b64 vcc, exec, s[84:85]
	v_mul_f32_e32 v103, v139, v139
	v_mul_f32_e32 v104, v141, v141
	v_fmac_f32_e32 v103, v138, v138
	v_fmac_f32_e32 v104, v140, v140
	v_add_f32_e32 v103, v103, v104
	v_mul_f32_e32 v104, v93, v93
	v_mul_f32_e32 v105, v95, v95
	v_fmac_f32_e32 v104, v92, v92
	v_fmac_f32_e32 v105, v94, v94
	v_add_f32_e32 v104, v104, v105
	v_add_f32_e32 v103, v103, v104
	v_mul_f32_e32 v104, v61, v61
	v_mul_f32_e32 v105, v63, v63
	v_fmac_f32_e32 v104, v60, v60
	v_fmac_f32_e32 v105, v62, v62
	v_and_b32_e32 v102, 64, v223
	v_add_f32_e32 v104, v104, v105
	v_xor_b32_e32 v96, 16, v223
	v_add_u32_e32 v102, 64, v102
	v_add_f32_e32 v103, v103, v104
	v_mul_f32_e32 v104, v29, v29
	v_mul_f32_e32 v105, v31, v31
	v_cmp_lt_i32_e32 vcc, v96, v102
	v_fmac_f32_e32 v104, v28, v28
	v_fmac_f32_e32 v105, v30, v30
	v_cndmask_b32_e32 v96, v223, v96, vcc
	v_add_f32_e32 v104, v104, v105
	v_lshlrev_b32_e32 v96, 2, v96
	v_add_f32_e32 v103, v103, v104
	ds_bpermute_b32 v104, v96, v103
	v_xor_b32_e32 v105, 32, v223
	v_cmp_lt_i32_e32 vcc, v105, v102
	s_lshl_b32 s4, s4, 2
	s_waitcnt lgkmcnt(0)
	v_add_f32_e32 v103, v103, v104
	v_cndmask_b32_e32 v102, v223, v105, vcc
	v_lshlrev_b32_e32 v102, 2, v102
	ds_bpermute_b32 v104, v102, v103
	s_add_i32 s4, s4, 0
	s_and_saveexec_b64 s[12:13], s[44:45]
	s_cbranch_execz .LBB0_418
	s_waitcnt lgkmcnt(0)
	v_add_f32_e32 v103, v103, v104
	v_lshl_add_u32 v104, v148, 4, s4
	ds_write_b32 v104, v103
